# v82 + one static priority raise for waves 4-7 during the O4 attention phase
# speedup vs baseline: 1.0027x; 1.0027x over previous
.LBB0_567:
	s_or_b64 exec, exec, s[0:1]
	v_readlane_b32 s2, v242, 4
	v_readfirstlane_b32 s1, v139
	v_readfirstlane_b32 s0, v138
	v_readlane_b32 s3, v242, 5
	s_waitcnt lgkmcnt(0)
	s_barrier
	s_nop 0
	v_readlane_b32 s2, v241, 10
	v_readlane_b32 s3, v241, 11
	s_andn2_b64 vcc, exec, s[2:3]
	s_cbranch_vccnz .LBB0_626
	v_lshrrev_b32_e32 v243, 8, v155
	s_nop 0
	v_readfirstlane_b32 vcc_lo, v243
	s_cmp_eq_u32 vcc_lo, 0
	s_cbranch_scc1 .Lo4prio_skip
	s_setprio 1
.Lo4prio_skip:
	s_add_u32 s8, s0, 0x8794000
	s_addc_u32 s9, s1, 0
	s_add_u32 s10, s0, 0xc694000
	s_addc_u32 s11, s1, 0
	s_add_u32 s18, s0, 0xd894000
	s_addc_u32 s19, s1, 0
	s_add_u32 s24, s0, 0xde94000
	s_addc_u32 s25, s1, 0
	s_add_u32 s26, s0, 0xed94000
	s_addc_u32 s27, s1, 0
	s_add_u32 s28, s0, 0xf194000
	s_addc_u32 s29, s1, 0
	s_add_u32 s14, s0, 0xed94080
	s_addc_u32 s15, s1, 0
	s_add_u32 s40, s0, 0xd897000
	s_addc_u32 s41, s1, 0
	s_add_u32 s42, s0, 0xf194080
	s_addc_u32 s43, s1, 0
	s_add_u32 s50, s0, 0xde97000
	v_readlane_b32 s0, v241, 34
	s_addc_u32 s51, s1, 0
	s_mov_b32 s52, s0
	s_mov_b32 s30, s92
	s_branch .LBB0_573

.LBB0_626:
	s_setprio 0
	s_waitcnt vmcnt(0)
	s_waitcnt vmcnt(63) expcnt(7) lgkmcnt(15)
	s_barrier
	s_and_saveexec_b64 s[0:1], s[94:95]
	s_cbranch_execz .LBB0_674
	s_waitcnt vmcnt(0) expcnt(0) lgkmcnt(0)
	buffer_inv sc1
	ds_read_b32 v2, v164
	ds_read_b32 v0, v165
	s_waitcnt lgkmcnt(1)
	v_cmp_ne_u32_e32 vcc, 0, v2
	s_cbranch_vccnz .LBB0_642
	s_mov_b32 s8, 1
	s_branch .LBB0_630
